# nontemporal hint on the read-once Q fragment loads of both attention bodies
# baseline (speedup 1.0000x reference)
; __device__ __forceinline__ void attn_na(unsigned char* lds, const int unit, const bf16_t* __restrict__ QKG, const bf16_t* __restrict__ Vt, bf16_t* __restrict__ Oout, const float* __restrict__ btab) {
;     int tid = threadIdx.x; asm volatile("" : "+v"(tid));
;     const int lane = tid & 63, wid = __builtin_amdgcn_readfirstlane(tid >> 6), q31 = lane & 31, hi = lane >> 5;
;     const int R = unit & 15, hd = (unit >> 4) & 7, b = unit >> 7;
;     const int rp = wid >> 2, j = wid & 3, ra = 4 * R + 2 * rp, rq = ra + (q31 >> 4), ccol = 16 * j + (q31 & 15), qtok = 64 * rq + ccol;
;     const int c0 = j == 0 ? 0 : (j == 1 ? 8 : (j == 2 ? 24 : 32));
;     const int kcol0 = C_KB + 128 * hd, vrow0 = 256 + 128 * hd;
;     const int r_lo = clampi(4 * R - 4, 0, 56), r_hi = clampi(4 * R - 1, 0, 56) + 8, kt0 = 64 * r_lo, nt = r_hi - r_lo, nst = (nt + 1) >> 1;
;     const int wa_lo = clampi(ra - 4, 0, 56), wa_hi = clampi(ra - 3, 0, 56) + 8;
;     const int rsq = clampi(rq - 4, 0, 56), cs = clampi(ccol - 8, 0, 48);
;     bf16x8 qf[8];
;     { const bf16_t* qp = QKG + (size_t)(b * SEQ + qtok) * QKG_LD + C_QB + 128 * hd + 8 * hi;
; #pragma unroll
;       for (int d0 = 0; d0 < 8; ++d0) qf[d0] = *(const bf16x8*)(qp + 16 * d0); }
;     float* tab = (float*)(lds + OFF_TAB);
;     for (int i = tid; i < TAB_SENT + 48; i += 512) tab[i] = (i >= 16 && i < 16 + 15 * 31) ? btab[hd * (15 * 31) + (i - 16)] * LOG2E : (i >= TAB_SENT - 16 ? -INFINITY : 0.0f);
.LBB0_584:
	s_add_i32 s0, s4, 0xfffffe00
	s_lshl_b32 s20, s0, 2
	s_ashr_i32 s21, s7, 7
	s_and_b32 s25, s20, 60
	s_and_b32 s27, s21, -2
	v_and_b32_e32 v7, 15, v2
	s_lshl_b32 s19, s0, 5
	s_add_i32 s27, s27, s25
	v_bfe_u32 v3, v2, 4, 1
	v_lshl_or_b32 v5, s6, 4, v7
	s_and_b32 s26, s19, 0x3000
	v_or_b32_e32 v4, s27, v3
	v_or_b32_e32 v0, s26, v5
	s_bfe_u32 s5, s4, 0x30004
	s_waitcnt vmcnt(22)
	v_lshl_add_u32 v148, v4, 6, v0
	v_mov_b64_e32 v[10:11], s[84:85]
	v_bfe_u32 v8, v2, 5, 1
	v_mad_i64_i32 v[10:11], s[0:1], v148, s88, v[10:11]
	s_lshl_b32 s60, s5, 8
	v_lshl_add_u64 v[10:11], v[10:11], 0, s[60:61]
	s_waitcnt vmcnt(21)
	v_lshlrev_b32_e32 v152, 4, v8
	v_mov_b32_e32 v153, v1
	v_lshl_add_u64 v[10:11], v[10:11], 0, v[152:153]
	global_load_dwordx4 v[84:87], v[10:11], off offset:2560 nt
	global_load_dwordx4 v[88:91], v[10:11], off offset:2592 nt
	global_load_dwordx4 v[92:95], v[10:11], off offset:2624 nt
	global_load_dwordx4 v[96:99], v[10:11], off offset:2656 nt
	global_load_dwordx4 v[100:103], v[10:11], off offset:2688 nt
	global_load_dwordx4 v[104:107], v[10:11], off offset:2720 nt
	global_load_dwordx4 v[108:111], v[10:11], off offset:2752 nt
	global_load_dwordx4 v[112:115], v[10:11], off offset:2784 nt
	s_movk_i32 s0, 0x2b0
	v_cmp_gt_i32_e32 vcc, s0, v2
	s_and_saveexec_b64 s[0:1], vcc
	s_cbranch_execz .LBB0_591
	s_mul_i32 s6, s5, 0x1d1
	v_readlane_b32 s7, v254, 44
	s_add_i32 s6, s6, -16
	s_mov_b64 s[12:13], 0
	v_lshl_add_u32 v6, v2, 2, s7
	v_mov_b32_e32 v9, v2
	s_branch .LBB0_587

; __device__ __forceinline__ int pi32(int r) { return (r & 19) | ((r & 4) << 1) | ((r & 8) >> 1); }
; __device__ __forceinline__ void attn_win(unsigned char* lds, const int unit, const bf16_t* __restrict__ QKG, const bf16_t* __restrict__ Vt, bf16_t* __restrict__ Oout, const float* __restrict__ sink) {
;     int tid = threadIdx.x; asm volatile("" : "+v"(tid));
;     const int lane = tid & 63, wid = __builtin_amdgcn_readfirstlane(tid >> 6), q31 = lane & 31, hi = lane >> 5;
;     const int qc = unit & 63, g = (unit >> 6) & 1, b = unit >> 7;
;     const int head = 4 * g + (wid >> 1), qbase = 64 * qc + 32 * (wid & 1), qtok = qbase + q31, kcol0 = C_KA + 128 * g, vrow0 = 128 * g;
;     int lo = 64 * qc - 128, hiE = 64 * qc + 192; lo = lo < 0 ? 0 : lo; hiE = hiE > SEQ ? SEQ : hiE; const int kt0 = lo, nt = (hiE - lo) >> 6, nst = (nt + 1) >> 1;
;     bf16x8 qf[8];
;     { const bf16_t* qp = QKG + (size_t)(b * SEQ + qtok) * QKG_LD + C_QA + 128 * head + 8 * hi;
; #pragma unroll
;       for (int d0 = 0; d0 < 8; ++d0) qf[d0] = *(const bf16x8*)(qp + 16 * d0); }
;     float m_run = sink[head] * LOG2E, l_run = hi == 0 ? 1.0f : 0.0f;
;     f32x16 o[4];
; #pragma unroll
;     for (int i = 0; i < 4; ++i) o[i] = f32x16{};
;     ATT_STAGE_DECL()
;     const int ka_off = pi32(q31) * KROW + hi * 16, va_off = q31 * VROW + hi * 16;
.LBB0_606:
	s_and_b64 vcc, exec, s[0:1]
	s_cbranch_vccz .LBB0_566
	v_mov_b32_e32 v3, v202
	s_bfe_u32 s7, s4, 0x10006
	v_readfirstlane_b32 s0, v3
	s_lshl_b32 s1, s7, 2
	s_ashr_i32 s5, s0, 7
	s_add_i32 s18, s5, s1
	s_lshl_b32 s1, s4, 6
	s_and_b32 s20, s1, 0xfc0
	s_lshr_b32 s0, s0, 1
	v_sub_u32_e64 v0, s20, v210 clamp
	s_and_b32 s11, s0, 32
	s_min_u32 s0, s20, 0xf40
	v_readfirstlane_b32 s1, v0
	s_sub_i32 s0, s0, s1
	s_addk_i32 s0, 0xc0
	v_and_b32_e32 v2, 31, v3
	s_or_b32 s9, s11, s20
	s_ashr_i32 s5, s0, 6
	s_lshl_b32 s0, s4, 5
	v_bfe_u32 v4, v3, 5, 1
	v_or_b32_e32 v5, s9, v2
	s_add_i32 s6, s5, 1
	s_and_b32 s12, s0, 0xfffff000
	s_lshl_b32 s0, s18, 7
	v_or_b32_e32 v182, s12, v5
	s_ashr_i32 s1, s0, 31
	s_ashr_i32 s6, s6, 1
	v_cmp_eq_u32_e32 vcc, 0, v4
	v_ashrrev_i32_e32 v183, 31, v182
	s_cmp_lt_i32 s6, 1
	v_cndmask_b32_e64 v177, 0, 1.0, vcc
	v_lshlrev_b32_e32 v176, 3, v4
	s_cbranch_scc1 .LBB0_564
	v_ashrrev_i32_e32 v16, 4, v3
	v_or_b32_e32 v5, s12, v0
	v_add_u32_e32 v5, v5, v16
	v_mov_b64_e32 v[6:7], s[84:85]
	v_lshl_add_u32 v17, s7, 7, v16
	v_mov_b64_e32 v[10:11], s[30:31]
	s_mov_b32 s21, 0x8100
	v_mad_i64_i32 v[8:9], s[16:17], v5, s88, v[6:7]
	v_mad_i64_i32 v[10:11], s[16:17], v17, s21, v[10:11]
	s_ashr_i32 s13, s12, 31
	s_ashr_i32 s19, s18, 31
	s_lshl_b32 s60, s7, 8
	s_lshl_b64 s[16:17], s[12:13], 1
	s_lshl_b64 s[18:19], s[18:19], 2
	s_add_u32 s18, s22, s18
	v_lshlrev_b32_e32 v5, 4, v3
	s_addc_u32 s19, s23, s19
	v_and_b32_e32 v184, 0xf0, v5
	v_lshl_add_u64 v[10:11], v[10:11], 0, s[16:17]
	v_lshlrev_b32_e32 v0, 1, v0
	v_lshlrev_b32_e32 v186, 4, v4
	global_load_dword v18, v1, s[18:19]
	v_mad_i64_i32 v[4:5], s[18:19], v182, s88, v[6:7]
	v_mov_b32_e32 v185, v1
	v_lshl_add_u64 v[10:11], v[10:11], 0, v[0:1]
	v_lshl_add_u64 v[4:5], s[0:1], 1, v[4:5]
	v_mov_b32_e32 v187, v1
	v_lshl_add_u64 v[10:11], v[10:11], 0, v[184:185]
	v_lshl_add_u64 v[4:5], v[4:5], 0, v[186:187]
	s_mov_b32 s7, 0x306000
	global_load_dwordx4 v[112:115], v[4:5], off offset:224 nt
	global_load_dwordx4 v[116:119], v[4:5], off offset:192 nt
	global_load_dwordx4 v[120:123], v[4:5], off offset:160 nt
	global_load_dwordx4 v[124:127], v[4:5], off offset:128 nt
	global_load_dwordx4 v[128:131], v[4:5], off offset:96 nt
	global_load_dwordx4 v[132:135], v[4:5], off offset:64 nt
	global_load_dwordx4 v[136:139], v[4:5], off offset:32 nt
	global_load_dwordx4 v[140:143], v[4:5], off nt
	v_add_co_u32_e32 v4, vcc, s7, v10
	s_mov_b32 s7, 0x204000
	s_nop 0
	v_addc_co_u32_e32 v5, vcc, 0, v11, vcc
	v_add_co_u32_e32 v6, vcc, s7, v10
	s_mov_b32 s7, 0x102000
	s_nop 0
	v_addc_co_u32_e32 v7, vcc, 0, v11, vcc
	v_lshl_add_u64 v[8:9], v[8:9], 0, s[60:61]
	global_load_dwordx4 v[160:163], v[4:5], off
	global_load_dwordx4 v[156:159], v[6:7], off
	v_add_co_u32_e32 v4, vcc, s7, v10
	v_lshl_add_u64 v[8:9], v[8:9], 0, v[184:185]
	s_nop 0
	v_addc_co_u32_e32 v5, vcc, 0, v11, vcc
	s_mov_b32 s7, 0x15c000
	v_add_co_u32_e32 v6, vcc, s7, v8
	s_mov_b32 s7, 0xe8000
	s_nop 0
	v_addc_co_u32_e32 v7, vcc, 0, v9, vcc
	v_add_co_u32_e32 v12, vcc, s7, v8
	s_mov_b32 s7, 0x74000
	s_nop 0
	v_addc_co_u32_e32 v13, vcc, 0, v9, vcc
	v_add_co_u32_e32 v14, vcc, s7, v8
	s_min_u32 s13, s20, 0x80
	s_nop 0
	v_addc_co_u32_e32 v15, vcc, 0, v9, vcc
	global_load_dwordx4 v[152:155], v[12:13], off offset:2048
	global_load_dwordx4 v[148:151], v[14:15], off offset:2048
	global_load_dwordx4 v[168:171], v[10:11], off
	global_load_dwordx4 v[144:147], v[8:9], off offset:2048
	global_load_dwordx4 v[172:175], v[4:5], off
	global_load_dwordx4 v[164:167], v[6:7], off offset:2048
	v_lshlrev_b32_e32 v5, 1, v2
	v_mul_u32_u24_e32 v187, 0x110, v2
	v_add_u32_e32 v2, s13, v2
	s_movk_i32 s10, 0x110
	v_sub_u32_e32 v2, v176, v2
	v_mul_lo_u32 v192, v16, s10
	s_add_i32 s10, s13, s11
	v_subrev_u32_e32 v194, s11, v2
	s_sub_i32 s11, s20, s13
	s_lshl_b32 s4, s4, 2
	v_and_b32_e32 v4, 19, v3
	v_lshrrev_b32_e32 v3, 1, v3
	s_addk_i32 s9, 0x41
	s_sub_i32 s10, 0, s10
	s_add_i32 s11, s11, 64
	s_add_i32 s20, s20, s12
	s_and_b32 s4, s4, 0x100
	v_and_b32_e32 v5, 8, v5
	v_and_b32_e32 v3, 4, v3
	v_add_u32_e32 v2, s20, v16
	s_add_u32 s12, s74, s4
	v_or3_b32 v3, v4, v5, v3
	v_subrev_u32_e32 v4, s13, v2
	s_addc_u32 s13, s75, 0
	v_mul_u32_u24_e32 v193, 0x110, v3
	v_mov_b64_e32 v[2:3], s[12:13]
	v_mad_i64_i32 v[188:189], s[12:13], v4, s88, v[2:3]
	v_lshl_add_u64 v[2:3], s[74:75], 0, v[0:1]
	v_lshl_add_u64 v[2:3], v[2:3], 0, s[16:17]
	v_mov_b32_e32 v14, v1
	v_mov_b32_e32 v15, v1
	v_mad_i64_i32 v[190:191], s[12:13], v17, s21, v[2:3]
	v_mov_b32_e32 v0, v1
	s_waitcnt vmcnt(16)
	v_mul_f32_e32 v195, 0x3fb8aa3b, v18
	v_mov_b32_e32 v2, v1
	v_mov_b32_e32 v3, v1
	v_mov_b32_e32 v4, v1
	v_mov_b32_e32 v5, v1
	v_mov_b32_e32 v6, v1
	v_mov_b32_e32 v7, v1
	v_mov_b32_e32 v8, v1
	v_mov_b32_e32 v9, v1
	v_mov_b32_e32 v10, v1
	v_mov_b32_e32 v11, v1
	v_mov_b32_e32 v12, v1
	v_mov_b32_e32 v13, v1
	v_mov_b64_e32 v[30:31], v[14:15]
	v_mov_b64_e32 v[46:47], v[14:15]
	v_mov_b64_e32 v[62:63], v[14:15]
	v_mov_b64_e32 v[78:79], v[14:15]
	s_mov_b32 s7, 1
	s_mov_b32 s8, 0
	v_mov_b64_e32 v[28:29], v[12:13]
	v_mov_b64_e32 v[26:27], v[10:11]
	v_mov_b64_e32 v[24:25], v[8:9]
	v_mov_b64_e32 v[22:23], v[6:7]
	v_mov_b64_e32 v[20:21], v[4:5]
	v_mov_b64_e32 v[18:19], v[2:3]
	v_mov_b64_e32 v[16:17], v[0:1]
	v_mov_b64_e32 v[44:45], v[12:13]
	v_mov_b64_e32 v[42:43], v[10:11]
	v_mov_b64_e32 v[40:41], v[8:9]
	v_mov_b64_e32 v[38:39], v[6:7]
	v_mov_b64_e32 v[36:37], v[4:5]
	v_mov_b64_e32 v[34:35], v[2:3]
	v_mov_b64_e32 v[32:33], v[0:1]
	v_mov_b64_e32 v[60:61], v[12:13]
	v_mov_b64_e32 v[58:59], v[10:11]
	v_mov_b64_e32 v[56:57], v[8:9]
	v_mov_b64_e32 v[54:55], v[6:7]
	v_mov_b64_e32 v[52:53], v[4:5]
	v_mov_b64_e32 v[50:51], v[2:3]
	v_mov_b64_e32 v[48:49], v[0:1]
	v_mov_b64_e32 v[76:77], v[12:13]
	v_mov_b64_e32 v[74:75], v[10:11]
	v_mov_b64_e32 v[72:73], v[8:9]
	v_mov_b64_e32 v[70:71], v[6:7]
	v_mov_b64_e32 v[68:69], v[4:5]
	v_mov_b64_e32 v[66:67], v[2:3]
	v_mov_b64_e32 v[64:65], v[0:1]
	s_mov_b32 s4, 0
	s_branch .LBB0_611
